# flat per-XCC-sharded grid barrier after GEMM phases (write-through stores), on top of norm fast path
# baseline (speedup 1.0000x reference)
.LBB0_605:
	s_waitcnt vmcnt(0)
	s_waitcnt vmcnt(0) lgkmcnt(0)
	s_barrier
	s_bitcmp1_b32 0xd5b56, s3
	s_cbranch_scc1 .Lflat_bar
	s_and_saveexec_b64 s[4:5], s[88:89]
	v_readlane_b32 s22, v249, 57
	v_readlane_b32 s24, v249, 59
	v_readlane_b32 s26, v249, 61
	v_readlane_b32 s28, v249, 63
	v_readlane_b32 s30, v248, 1
	v_readlane_b32 s34, v248, 3
	v_readlane_b32 s36, v248, 5
	v_readlane_b32 s23, v249, 58
	v_readlane_b32 s25, v249, 60
	v_readlane_b32 s27, v249, 62
	v_readlane_b32 s29, v248, 0
	v_readlane_b32 s31, v248, 2
	v_readlane_b32 s35, v248, 4
	v_readlane_b32 s37, v248, 6
	v_readlane_b32 s21, v248, 7
	s_cbranch_execz .LBB0_133
	v_readlane_b32 s6, v249, 50
	s_waitcnt vmcnt(0) expcnt(0) lgkmcnt(0)
	s_nop 0
	v_mov_b32_e32 v0, s6
	ds_read_b32 v3, v0
	v_readlane_b32 s6, v249, 51
	s_waitcnt lgkmcnt(0)
	v_cmp_ne_u32_e32 vcc, 0, v3
	v_mov_b32_e32 v0, s6
	ds_read_b32 v2, v0
	s_cbranch_vccnz .LBB0_621
	s_mov_b32 s12, 1
	s_branch .LBB0_609

.Lflat_bar:
	s_and_saveexec_b64 s[4:5], s[88:89]
	s_cbranch_execz .LBB0_133
	v_readlane_b32 s8, v249, 35
	v_readlane_b32 s9, v249, 36
	v_readlane_b32 s22, v249, 57
	v_readlane_b32 s23, v249, 58
	v_readlane_b32 s21, v248, 7
	s_lshl_b32 s6, 2, s3
	s_add_i32 s6, s6, -1
	s_and_b32 s6, s6, 0xd5b56
	s_bcnt1_i32_b32 s6, s6
	s_mul_i32 s20, s6, s21
	s_add_u32 s6, s22, 0x1a80
	s_addc_u32 s7, s23, 0
	v_mov_b32_e32 v2, 1
	s_mov_b32 s12, 0
	s_nop 4
	global_atomic_add v1, v2, s[8:9] offset:128
.Lflat_poll:
	global_load_dword v2, v1, s[6:7] offset:-2048 sc1
	global_load_dword v3, v1, s[6:7] offset:-1792 sc1
	global_load_dword v4, v1, s[6:7] offset:-1536 sc1
	global_load_dword v5, v1, s[6:7] offset:-1280 sc1
	global_load_dword v6, v1, s[6:7] offset:-1024 sc1
	global_load_dword v7, v1, s[6:7] offset:-768 sc1
	global_load_dword v8, v1, s[6:7] offset:-512 sc1
	global_load_dword v9, v1, s[6:7] offset:-256 sc1
	global_load_dword v10, v1, s[6:7] offset:0 sc1
	global_load_dword v11, v1, s[6:7] offset:256 sc1
	global_load_dword v12, v1, s[6:7] offset:512 sc1
	global_load_dword v13, v1, s[6:7] offset:768 sc1
	global_load_dword v14, v1, s[6:7] offset:1024 sc1
	global_load_dword v15, v1, s[6:7] offset:1280 sc1
	global_load_dword v16, v1, s[6:7] offset:1536 sc1
	global_load_dword v17, v1, s[6:7] offset:1792 sc1
	s_waitcnt vmcnt(0)
	v_add_u32_e32 v2, v2, v3
	v_add_u32_e32 v2, v2, v4
	v_add_u32_e32 v2, v2, v5
	v_add_u32_e32 v2, v2, v6
	v_add_u32_e32 v2, v2, v7
	v_add_u32_e32 v2, v2, v8
	v_add_u32_e32 v2, v2, v9
	v_add_u32_e32 v2, v2, v10
	v_add_u32_e32 v2, v2, v11
	v_add_u32_e32 v2, v2, v12
	v_add_u32_e32 v2, v2, v13
	v_add_u32_e32 v2, v2, v14
	v_add_u32_e32 v2, v2, v15
	v_add_u32_e32 v2, v2, v16
	v_add_u32_e32 v2, v2, v17
	s_nop 1
	v_readfirstlane_b32 s10, v2
	s_cmp_ge_u32 s10, s20
	s_cbranch_scc1 .Lflat_done
	s_sleep 1
	s_add_i32 s12, s12, 1
	s_cmp_lt_u32 s12, 0x800
	s_cbranch_scc1 .Lflat_poll
.Lflat_done:
	buffer_inv sc1
	s_waitcnt vmcnt(0)
	s_branch .LBB0_133
